# grid barrier after mixer out_ln and after ffn_in replaced by an 8-workgroup panel-group sync: write-through H/x/ACT stores, one epoch word per workgroup polled by its group
# speedup vs baseline: 1.0282x; 1.0071x over previous
.LBB0_39:
	s_or_b64 exec, exec, s[30:31]
	s_add_u32 s40, s44, 0x3000
	s_addc_u32 s41, s45, 0
	s_add_u32 s30, s44, 0x4000
	s_addc_u32 s31, s45, 0
	v_lshlrev_b64 v[44:45], 2, v[96:97]
	v_lshl_add_u64 v[40:41], s[0:1], 0, v[44:45]
	v_lshl_add_u64 v[42:43], s[4:5], 0, v[44:45]
	v_lshl_add_u64 v[16:17], s[40:41], 0, v[44:45]
	v_lshl_add_u64 v[44:45], s[30:31], 0, v[44:45]
	s_waitcnt lgkmcnt(0)
	s_barrier
	global_load_dwordx4 v[0:3], v[40:41], off offset:16
	global_load_dwordx4 v[8:11], v[40:41], off
	global_load_dwordx4 v[12:15], v[42:43], off offset:16
	global_load_dwordx4 v[20:23], v[42:43], off
	global_load_dwordx4 v[4:7], v[16:17], off offset:16
	s_nop 0
	global_load_dwordx4 v[16:19], v[16:17], off
	s_nop 0
	global_load_dwordx4 v[58:61], v[44:45], off offset:16
	s_nop 0
	global_load_dwordx4 v[44:47], v[44:45], off
	v_or_b32_e32 v32, v110, v108
	s_add_i32 s33, 0, 0x24000
	v_lshl_add_u32 v112, v32, 3, s33
	v_add_u32_e32 v62, s63, v32
	v_ashrrev_i32_e32 v63, 31, v62
	v_lshlrev_b64 v[62:63], 11, v[62:63]
	s_waitcnt vmcnt(1)
	v_pk_add_f32 v[106:107], v[58:59], 1.0 op_sel_hi:[1,0]
	s_waitcnt vmcnt(0)
	v_pk_add_f32 v[108:109], v[46:47], 1.0 op_sel_hi:[1,0]
	ds_read_b32 v33, v112
	ds_read_b64 v[46:47], v112
	v_pk_add_f32 v[110:111], v[44:45], 1.0 op_sel_hi:[1,0]
	v_pk_add_f32 v[44:45], v[60:61], 1.0 op_sel_hi:[1,0]
	s_waitcnt lgkmcnt(1)
	v_sub_f32_e32 v59, v101, v33
	v_sub_f32_e32 v58, v100, v33
	s_waitcnt lgkmcnt(0)
	v_pk_mul_f32 v[58:59], v[58:59], v[46:47] op_sel:[0,1]
	v_sub_f32_e32 v61, v99, v33
	v_sub_f32_e32 v60, v98, v33
	v_pk_fma_f32 v[98:99], v[10:11], v[58:59], v[22:23]
	v_sub_f32_e32 v59, v103, v33
	v_sub_f32_e32 v58, v102, v33
	v_pk_mul_f32 v[60:61], v[60:61], v[46:47] op_sel:[0,1]
	v_pk_mul_f32 v[58:59], v[46:47], v[58:59] op_sel:[1,0]
	v_pk_fma_f32 v[100:101], v[8:9], v[60:61], v[20:21]
	v_sub_f32_e32 v61, v105, v33
	v_sub_f32_e32 v60, v104, v33
	v_pk_fma_f32 v[102:103], v[2:3], v[58:59], v[14:15]
	v_cvt_pk_bf16_f32 v59, v98, v99
	v_pk_fma_f32 v[98:99], v[108:109], v[98:99], v[18:19]
	v_pk_mul_f32 v[60:61], v[46:47], v[60:61] op_sel:[1,0]
	v_cvt_pk_bf16_f32 v115, v98, v99
	v_pk_fma_f32 v[98:99], v[44:45], v[102:103], v[6:7]
	v_pk_fma_f32 v[104:105], v[0:1], v[60:61], v[12:13]
	v_cvt_pk_bf16_f32 v61, v102, v103
	v_cvt_pk_bf16_f32 v117, v98, v99
	v_lshl_add_u64 v[98:99], s[24:25], 0, v[62:63]
	v_lshlrev_b64 v[102:103], 1, v[96:97]
	v_cvt_pk_bf16_f32 v58, v100, v101
	v_cvt_pk_bf16_f32 v60, v104, v105
	v_pk_fma_f32 v[100:101], v[110:111], v[100:101], v[16:17]
	v_lshl_add_u64 v[98:99], v[98:99], 0, v[102:103]
	v_cvt_pk_bf16_f32 v114, v100, v101
	v_pk_fma_f32 v[100:101], v[106:107], v[104:105], v[4:5]
	global_store_dwordx4 v[98:99], v[58:61], off sc1
	v_cvt_pk_bf16_f32 v116, v100, v101
	v_or_b32_e32 v33, 16, v32
	v_lshl_add_u64 v[58:59], s[28:29], 0, v[62:63]
	v_lshl_add_u64 v[100:101], v[58:59], 0, v[102:103]
	global_store_dwordx4 v[100:101], v[114:117], off sc1
	v_lshl_add_u32 v97, v33, 3, s33
	v_add_u32_e32 v60, s63, v33
	ds_read_b32 v33, v97
	ds_read_b64 v[58:59], v97
	v_ashrrev_i32_e32 v61, 31, v60
	s_waitcnt lgkmcnt(1)
	v_sub_f32_e32 v89, v89, v33
	v_sub_f32_e32 v88, v88, v33
	v_sub_f32_e32 v63, v91, v33
	v_sub_f32_e32 v62, v90, v33
	s_waitcnt lgkmcnt(0)
	v_pk_mul_f32 v[88:89], v[88:89], v[58:59] op_sel:[0,1]
	v_pk_mul_f32 v[62:63], v[62:63], v[58:59] op_sel:[0,1]
	v_pk_fma_f32 v[104:105], v[8:9], v[88:89], v[20:21]
	v_sub_f32_e32 v89, v95, v33
	v_sub_f32_e32 v88, v94, v33
	v_sub_f32_e32 v91, v93, v33
	v_sub_f32_e32 v90, v92, v33
	v_pk_fma_f32 v[62:63], v[10:11], v[62:63], v[22:23]
	v_pk_mul_f32 v[90:91], v[58:59], v[90:91] op_sel:[1,0]
	v_pk_mul_f32 v[88:89], v[58:59], v[88:89] op_sel:[1,0]
	v_pk_fma_f32 v[114:115], v[0:1], v[90:91], v[12:13]
	v_pk_fma_f32 v[94:95], v[2:3], v[88:89], v[14:15]
	v_cvt_pk_bf16_f32 v89, v62, v63
	v_pk_fma_f32 v[62:63], v[108:109], v[62:63], v[18:19]
	v_pk_fma_f32 v[92:93], v[110:111], v[104:105], v[16:17]
	v_cvt_pk_bf16_f32 v91, v94, v95
	v_cvt_pk_bf16_f32 v92, v92, v93
	v_cvt_pk_bf16_f32 v93, v62, v63
	v_pk_fma_f32 v[62:63], v[44:45], v[94:95], v[6:7]
	v_pk_fma_f32 v[94:95], v[106:107], v[114:115], v[4:5]
	v_cvt_pk_bf16_f32 v88, v104, v105
	v_cvt_pk_bf16_f32 v94, v94, v95
	v_cvt_pk_bf16_f32 v95, v62, v63
	v_lshlrev_b64 v[62:63], 11, v[60:61]
	v_lshl_add_u64 v[60:61], s[24:25], 0, v[62:63]
	v_lshl_add_u64 v[62:63], s[28:29], 0, v[62:63]
	v_cvt_pk_bf16_f32 v90, v114, v115
	v_lshl_add_u64 v[60:61], v[60:61], 0, v[102:103]
	v_lshl_add_u64 v[62:63], v[62:63], 0, v[102:103]
	v_or_b32_e32 v33, 32, v32
	global_store_dwordx4 v[60:61], v[88:91], off sc1
	global_store_dwordx4 v[62:63], v[92:95], off sc1
	v_lshl_add_u32 v59, v33, 3, s33
	v_or_b32_e32 v32, 48, v32
	v_add_u32_e32 v94, s63, v33
	ds_read_b32 v33, v59
	ds_read_b64 v[88:89], v59
	v_ashrrev_i32_e32 v95, 31, v94
	v_lshl_add_u32 v47, v32, 3, s33
	v_sub_f32_e32 v65, v65, v58
	s_waitcnt lgkmcnt(1)
	v_sub_f32_e32 v75, v75, v33
	v_sub_f32_e32 v74, v74, v33
	v_sub_f32_e32 v73, v73, v33
	v_sub_f32_e32 v72, v72, v33
	s_waitcnt lgkmcnt(0)
	v_pk_mul_f32 v[74:75], v[74:75], v[88:89] op_sel:[0,1]
	v_pk_mul_f32 v[72:73], v[72:73], v[88:89] op_sel:[0,1]
	v_pk_fma_f32 v[90:91], v[10:11], v[74:75], v[22:23]
	v_sub_f32_e32 v75, v79, v33
	v_sub_f32_e32 v74, v78, v33
	v_sub_f32_e32 v77, v77, v33
	v_sub_f32_e32 v76, v76, v33
	v_pk_fma_f32 v[72:73], v[8:9], v[72:73], v[20:21]
	v_pk_mul_f32 v[76:77], v[88:89], v[76:77] op_sel:[1,0]
	v_pk_mul_f32 v[74:75], v[88:89], v[74:75] op_sel:[1,0]
	v_pk_fma_f32 v[92:93], v[0:1], v[76:77], v[12:13]
	v_pk_fma_f32 v[78:79], v[2:3], v[74:75], v[14:15]
	v_cvt_pk_bf16_f32 v74, v72, v73
	v_pk_fma_f32 v[72:73], v[110:111], v[72:73], v[16:17]
	v_cvt_pk_bf16_f32 v75, v90, v91
	v_cvt_pk_bf16_f32 v77, v78, v79
	v_pk_fma_f32 v[104:105], v[108:109], v[90:91], v[18:19]
	v_cvt_pk_bf16_f32 v90, v72, v73
	v_pk_fma_f32 v[72:73], v[44:45], v[78:79], v[6:7]
	v_pk_fma_f32 v[78:79], v[106:107], v[92:93], v[4:5]
	v_cvt_pk_bf16_f32 v76, v92, v93
	v_cvt_pk_bf16_f32 v92, v78, v79
	v_lshlrev_b64 v[78:79], 11, v[94:95]
	v_cvt_pk_bf16_f32 v93, v72, v73
	v_lshl_add_u64 v[72:73], s[24:25], 0, v[78:79]
	v_lshl_add_u64 v[72:73], v[72:73], 0, v[102:103]
	global_store_dwordx4 v[72:73], v[74:77], off sc1
	v_cvt_pk_bf16_f32 v91, v104, v105
	v_sub_f32_e32 v64, v64, v58
	v_lshl_add_u64 v[74:75], s[28:29], 0, v[78:79]
	v_lshl_add_u64 v[74:75], v[74:75], 0, v[102:103]
	global_store_dwordx4 v[74:75], v[90:93], off sc1
	v_add_u32_e32 v76, s63, v32
	ds_read_b32 v77, v47
	ds_read_b64 v[32:33], v47
	v_sub_f32_e32 v51, v51, v88
	v_sub_f32_e32 v50, v50, v88
	v_sub_f32_e32 v49, v49, v88
	s_waitcnt lgkmcnt(1)
	v_sub_f32_e32 v57, v57, v77
	v_sub_f32_e32 v56, v56, v77
	v_sub_f32_e32 v35, v35, v77
	v_sub_f32_e32 v34, v34, v77
	s_waitcnt lgkmcnt(0)
	v_pk_mul_f32 v[56:57], v[56:57], v[32:33] op_sel:[0,1]
	v_pk_mul_f32 v[34:35], v[34:35], v[32:33] op_sel:[0,1]
	v_pk_fma_f32 v[10:11], v[10:11], v[56:57], v[22:23]
	v_sub_f32_e32 v23, v37, v77
	v_sub_f32_e32 v22, v36, v77
	v_pk_fma_f32 v[8:9], v[8:9], v[34:35], v[20:21]
	v_sub_f32_e32 v21, v39, v77
	v_sub_f32_e32 v20, v38, v77
	v_pk_mul_f32 v[22:23], v[32:33], v[22:23] op_sel:[1,0]
	v_pk_mul_f32 v[20:21], v[32:33], v[20:21] op_sel:[1,0]
	v_pk_fma_f32 v[12:13], v[0:1], v[22:23], v[12:13]
	v_pk_fma_f32 v[14:15], v[2:3], v[20:21], v[14:15]
	v_cvt_pk_bf16_f32 v0, v8, v9
	v_cvt_pk_bf16_f32 v1, v10, v11
	v_pk_fma_f32 v[10:11], v[108:109], v[10:11], v[18:19]
	v_pk_fma_f32 v[8:9], v[110:111], v[8:9], v[16:17]
	v_pk_fma_f32 v[4:5], v[106:107], v[12:13], v[4:5]
	v_ashrrev_i32_e32 v77, 31, v76
	v_cvt_pk_bf16_f32 v8, v8, v9
	v_cvt_pk_bf16_f32 v9, v10, v11
	v_pk_fma_f32 v[6:7], v[44:45], v[14:15], v[6:7]
	v_cvt_pk_bf16_f32 v10, v4, v5
	v_lshlrev_b64 v[4:5], 11, v[76:77]
	v_cvt_pk_bf16_f32 v11, v6, v7
	v_lshl_add_u64 v[6:7], s[24:25], 0, v[4:5]
	v_cvt_pk_bf16_f32 v2, v12, v13
	v_cvt_pk_bf16_f32 v3, v14, v15
	v_lshl_add_u64 v[34:35], v[6:7], 0, v[102:103]
	global_store_dwordx4 v[34:35], v[0:3], off sc1
	v_sub_f32_e32 v48, v48, v88
	v_sub_f32_e32 v27, v27, v32
	v_lshl_add_u64 v[0:1], s[28:29], 0, v[4:5]
	v_lshl_add_u64 v[36:37], v[0:1], 0, v[102:103]
	v_or_b32_e32 v0, 32, v96
	v_ashrrev_i32_e32 v1, 31, v0
	v_lshlrev_b64 v[38:39], 2, v[0:1]
	global_store_dwordx4 v[36:37], v[8:11], off sc1
	global_load_dwordx4 v[4:7], v[40:41], off offset:144
	global_load_dwordx4 v[16:19], v[40:41], off offset:128
	global_load_dwordx4 v[12:15], v[42:43], off offset:144
	global_load_dwordx4 v[20:23], v[42:43], off offset:128
	v_lshl_add_u64 v[8:9], s[40:41], 0, v[38:39]
	v_lshl_add_u64 v[38:39], s[30:31], 0, v[38:39]
	global_load_dwordx4 v[0:3], v[8:9], off offset:16
	s_nop 0
	global_load_dwordx4 v[8:11], v[8:9], off
	s_nop 0
	global_load_dwordx4 v[76:79], v[38:39], off offset:16
	s_nop 0
	global_load_dwordx4 v[38:41], v[38:39], off
	ds_read_b32 v56, v112 offset:4
	v_sub_f32_e32 v26, v26, v32
	v_sub_f32_e32 v25, v25, v32
	v_sub_f32_e32 v24, v24, v32
	v_readlane_b32 s30, v254, 62
	v_readlane_b32 s31, v254, 63
	s_waitcnt vmcnt(0)
	v_pk_add_f32 v[42:43], v[40:41], 1.0 op_sel_hi:[1,0]
	v_pk_add_f32 v[44:45], v[38:39], 1.0 op_sel_hi:[1,0]
	v_pk_add_f32 v[38:39], v[78:79], 1.0 op_sel_hi:[1,0]
	v_pk_add_f32 v[40:41], v[76:77], 1.0 op_sel_hi:[1,0]
	v_sub_f32_e32 v77, v83, v46
	v_sub_f32_e32 v76, v82, v46
	v_sub_f32_e32 v79, v81, v46
	v_sub_f32_e32 v78, v80, v46
	s_waitcnt lgkmcnt(0)
	v_pk_mul_f32 v[78:79], v[78:79], v[56:57] op_sel_hi:[1,0]
	v_pk_mul_f32 v[76:77], v[76:77], v[56:57] op_sel_hi:[1,0]
	v_pk_fma_f32 v[82:83], v[16:17], v[78:79], v[20:21]
	v_pk_fma_f32 v[80:81], v[18:19], v[76:77], v[22:23]
	v_sub_f32_e32 v77, v85, v46
	v_sub_f32_e32 v76, v84, v46
	v_sub_f32_e32 v79, v87, v46
	v_sub_f32_e32 v78, v86, v46
	v_pk_mul_f32 v[78:79], v[56:57], v[78:79] op_sel_hi:[0,1]
	v_pk_mul_f32 v[56:57], v[56:57], v[76:77] op_sel_hi:[0,1]
	v_pk_fma_f32 v[56:57], v[6:7], v[56:57], v[14:15]
	v_pk_fma_f32 v[84:85], v[4:5], v[78:79], v[12:13]
	v_cvt_pk_bf16_f32 v76, v82, v83
	v_cvt_pk_bf16_f32 v77, v80, v81
	v_cvt_pk_bf16_f32 v78, v84, v85
	v_cvt_pk_bf16_f32 v79, v56, v57
	v_pk_fma_f32 v[86:87], v[42:43], v[80:81], v[10:11]
	v_pk_fma_f32 v[80:81], v[44:45], v[82:83], v[8:9]
	v_pk_fma_f32 v[56:57], v[38:39], v[56:57], v[2:3]
	v_pk_fma_f32 v[82:83], v[40:41], v[84:85], v[0:1]
	v_cvt_pk_bf16_f32 v80, v80, v81
	v_cvt_pk_bf16_f32 v81, v86, v87
	v_cvt_pk_bf16_f32 v82, v82, v83
	v_cvt_pk_bf16_f32 v83, v56, v57
	global_store_dwordx4 v[98:99], v[76:79], off offset:64 sc1
	global_store_dwordx4 v[100:101], v[80:83], off offset:64 sc1
	ds_read_b32 v46, v97 offset:4
	v_sub_f32_e32 v57, v67, v58
	v_sub_f32_e32 v56, v66, v58
	v_sub_f32_e32 v67, v69, v58
	v_sub_f32_e32 v66, v68, v58
	s_waitcnt lgkmcnt(0)
	v_pk_mul_f32 v[64:65], v[64:65], v[46:47] op_sel_hi:[1,0]
	v_pk_mul_f32 v[56:57], v[56:57], v[46:47] op_sel_hi:[1,0]
	v_pk_fma_f32 v[76:77], v[16:17], v[64:65], v[20:21]
	v_sub_f32_e32 v65, v71, v58
	v_sub_f32_e32 v64, v70, v58
	v_pk_fma_f32 v[56:57], v[18:19], v[56:57], v[22:23]
	v_pk_mul_f32 v[66:67], v[46:47], v[66:67] op_sel_hi:[0,1]
	v_pk_mul_f32 v[64:65], v[46:47], v[64:65] op_sel_hi:[0,1]
	v_pk_fma_f32 v[70:71], v[6:7], v[64:65], v[14:15]
	v_pk_fma_f32 v[78:79], v[4:5], v[66:67], v[12:13]
	v_cvt_pk_bf16_f32 v65, v56, v57
	v_pk_fma_f32 v[56:57], v[42:43], v[56:57], v[10:11]
	v_pk_fma_f32 v[68:69], v[44:45], v[76:77], v[8:9]
	v_cvt_pk_bf16_f32 v64, v76, v77
	v_cvt_pk_bf16_f32 v66, v78, v79
	v_cvt_pk_bf16_f32 v67, v70, v71
	v_cvt_pk_bf16_f32 v68, v68, v69
	v_cvt_pk_bf16_f32 v69, v56, v57
	v_pk_fma_f32 v[56:57], v[38:39], v[70:71], v[2:3]
	v_pk_fma_f32 v[70:71], v[40:41], v[78:79], v[0:1]
	s_nop 0
	v_cvt_pk_bf16_f32 v70, v70, v71
	v_cvt_pk_bf16_f32 v71, v56, v57
	global_store_dwordx4 v[60:61], v[64:67], off offset:64 sc1
	global_store_dwordx4 v[62:63], v[68:71], off offset:64 sc1
	ds_read_b32 v46, v59 offset:4
	s_waitcnt lgkmcnt(0)
	v_pk_mul_f32 v[48:49], v[48:49], v[46:47] op_sel_hi:[1,0]
	v_pk_mul_f32 v[50:51], v[50:51], v[46:47] op_sel_hi:[1,0]
	v_pk_fma_f32 v[58:59], v[16:17], v[48:49], v[20:21]
	v_pk_fma_f32 v[56:57], v[18:19], v[50:51], v[22:23]
	v_sub_f32_e32 v49, v55, v88
	v_sub_f32_e32 v48, v54, v88
	v_sub_f32_e32 v51, v53, v88
	v_sub_f32_e32 v50, v52, v88
	v_pk_mul_f32 v[50:51], v[46:47], v[50:51] op_sel_hi:[0,1]
	v_pk_mul_f32 v[48:49], v[46:47], v[48:49] op_sel_hi:[0,1]
	v_pk_fma_f32 v[54:55], v[6:7], v[48:49], v[14:15]
	v_pk_fma_f32 v[60:61], v[4:5], v[50:51], v[12:13]
	v_cvt_pk_bf16_f32 v49, v56, v57
	v_pk_fma_f32 v[56:57], v[42:43], v[56:57], v[10:11]
	v_pk_fma_f32 v[52:53], v[44:45], v[58:59], v[8:9]
	v_cvt_pk_bf16_f32 v48, v58, v59
	v_cvt_pk_bf16_f32 v50, v60, v61
	v_cvt_pk_bf16_f32 v51, v54, v55
	v_cvt_pk_bf16_f32 v52, v52, v53
	v_cvt_pk_bf16_f32 v53, v56, v57
	v_pk_fma_f32 v[56:57], v[38:39], v[54:55], v[2:3]
	v_pk_fma_f32 v[54:55], v[40:41], v[60:61], v[0:1]
	s_nop 0
	v_cvt_pk_bf16_f32 v54, v54, v55
	v_cvt_pk_bf16_f32 v55, v56, v57
	global_store_dwordx4 v[72:73], v[48:51], off offset:64 sc1
	global_store_dwordx4 v[74:75], v[52:55], off offset:64 sc1
	ds_read_b32 v46, v47 offset:4
	s_waitcnt lgkmcnt(0)
	v_pk_mul_f32 v[24:25], v[24:25], v[46:47] op_sel_hi:[1,0]
	v_pk_mul_f32 v[26:27], v[26:27], v[46:47] op_sel_hi:[1,0]
	v_pk_fma_f32 v[16:17], v[16:17], v[24:25], v[20:21]
	v_pk_fma_f32 v[18:19], v[18:19], v[26:27], v[22:23]
	v_sub_f32_e32 v21, v31, v32
	v_sub_f32_e32 v20, v30, v32
	v_sub_f32_e32 v23, v29, v32
	v_sub_f32_e32 v22, v28, v32
	v_pk_mul_f32 v[22:23], v[46:47], v[22:23] op_sel_hi:[0,1]
	v_pk_mul_f32 v[20:21], v[46:47], v[20:21] op_sel_hi:[0,1]
	v_pk_fma_f32 v[14:15], v[6:7], v[20:21], v[14:15]
	v_pk_fma_f32 v[12:13], v[4:5], v[22:23], v[12:13]
	v_cvt_pk_bf16_f32 v4, v16, v17
	v_cvt_pk_bf16_f32 v5, v18, v19
	v_cvt_pk_bf16_f32 v6, v12, v13
	v_cvt_pk_bf16_f32 v7, v14, v15
	v_pk_fma_f32 v[10:11], v[42:43], v[18:19], v[10:11]
	v_pk_fma_f32 v[8:9], v[44:45], v[16:17], v[8:9]
	v_pk_fma_f32 v[2:3], v[38:39], v[14:15], v[2:3]
	v_pk_fma_f32 v[0:1], v[40:41], v[12:13], v[0:1]
	v_cvt_pk_bf16_f32 v8, v8, v9
	v_cvt_pk_bf16_f32 v9, v10, v11
	v_cvt_pk_bf16_f32 v10, v0, v1
	v_cvt_pk_bf16_f32 v11, v2, v3
	global_store_dwordx4 v[34:35], v[4:7], off offset:64 sc1
	global_store_dwordx4 v[36:37], v[8:11], off offset:64 sc1
	s_load_dword s30, s[30:31], 0x0
	s_waitcnt lgkmcnt(0)
	s_add_i32 s56, s30, s56
	s_cmpk_gt_i32 s56, 0xff
	s_cbranch_scc1 .LBB0_151

.LBB0_1498:
	s_mov_b32 s4, 0x18c18c0
	s_lshr_b32 s4, s4, s54
	s_bitcmp1_b32 s4, 0
	s_cbranch_scc0 .Lgs_grid
	v_readlane_b32 s4, v254, 0
	s_and_b32 s5, s4, 31
	s_lshr_b32 s4, s4, 5
	s_lshl_b32 s24, s5, 3
	s_add_i32 s24, s24, s4
	s_lshl_b32 s24, s24, 2
	s_add_u32 s28, s52, 0x3600
	s_addc_u32 s29, s53, 0
	v_mov_b32_e32 v0, s24
	v_mov_b32_e32 v1, s54
	global_store_dword v0, v1, s[28:29] sc1
	buffer_inv sc1
	s_lshl_b32 s24, s5, 5
	v_mov_b32_e32 v0, s24
	s_mov_b32 s33, 0
.Lgs_loop:
	global_load_dwordx4 v[2:5], v0, s[28:29] sc1
	global_load_dwordx4 v[6:9], v0, s[28:29] offset:16 sc1
	s_waitcnt vmcnt(0)
	v_min_u32_e32 v2, v2, v3
	v_min_u32_e32 v4, v4, v5
	v_min_u32_e32 v6, v6, v7
	v_min_u32_e32 v8, v8, v9
	v_min_u32_e32 v2, v2, v4
	v_min_u32_e32 v6, v6, v8
	v_min_u32_e32 v2, v2, v6
	v_cmp_gt_u32_e32 vcc, s54, v2
	s_cbranch_vccz .Lnb_done
	s_sleep 1
	s_add_i32 s33, s33, 1
	s_cmp_lt_u32 s33, 0x4000
	s_cbranch_scc1 .Lgs_loop
	s_branch .Lnb_done
